# per-half check: static s_setprio 1 for waves 0-3 (older half) instead of 4-7 in S3/kv
# baseline (speedup 1.0000x reference)
; #define LAS __attribute__((address_space(3)))
; __device__ __forceinline__ void ssd_s3_phase(Frame& F, const bf16* xc, const bf16* xtile, const bf16* btok, const bf16* ctok, const bf16* zx, const float* dt, const float* a_log, const float* dsk, float* ssg, const bf16* states, bf16* ybuf) {
;     const int lane = F.lane, r = lane & 31, h2 = lane >> 5, li = F.wave >> 1, hhalf = F.wave & 1;
;     LAS float* cst = (LAS float*)(F.lds + RING_OFF);
;     LAS float* dtt = cst + 2048;
;     LAS float* ssw = dtt + 2048;
;     LAS float* TT = (LAS float*)(F.lds + RING_OFF + 20480) + F.wave * (32 * 36);
;     const int el = lane >> 1, eh = lane & 1;
;     for (int u = blockIdx.x; u < 64 * SSD_NG; u += F.G) {
;         const int c = u >> 3, g = u & 7, t0 = c * 128;
; #pragma unroll
;         for (int hh = 0; hh < 2; ++hh) { const int hl = F.wave * 2 + hh, h = g * 16 + hl; const float A = -__expf(a_log[h]);
.LBB0_544:
	s_cmpk_lt_u32 s94, 0x100
	s_cbranch_scc0 .Lprio_skip_a
	s_setprio 1
